# phase 6 rmsnorm pass hand-written: gains loaded once, next row prefetched, stores not waited on
# speedup vs baseline: 1.0053x; 1.0053x over previous
; __device__ __forceinline__ float bflo(unsigned w) { return __uint_as_float(w << 16); }
; __device__ __forceinline__ float bfhi(unsigned w) { return __uint_as_float(w & 0xffff0000u); }
; __device__ __forceinline__ void rms_row_b2b(const bf16_t* xrow, const float* g, bf16_t* orow, int lane) {
;     const u32x4* xr = (const u32x4*)xrow + lane; u32x4 w[4]; float s = 0.f;
; #pragma unroll
;     for (int j = 0; j < 4; ++j) { w[j] = xr[64 * j];
;         const float a0 = bflo(w[j].x), a1 = bfhi(w[j].x), a2 = bflo(w[j].y), a3 = bfhi(w[j].y), a4 = bflo(w[j].z), a5 = bfhi(w[j].z), a6 = bflo(w[j].w), a7 = bfhi(w[j].w);
;         s += ((a0 * a0 + a1 * a1) + (a2 * a2 + a3 * a3)) + ((a4 * a4 + a5 * a5) + (a6 * a6 + a7 * a7)); }
;     const float rstd = rsqrtf(wave_sum(s) * (1.f / DM) + EPS);
; __global__ void __launch_bounds__(512, 2) mega(Params p) {
;     ...
;         const int tid = opaque_tid(wave_s), lane = tid & 63, wave = tid >> 6;
;         const int gw = bx * 8 + wave, NGW = G * 8;
;         for (int m = gw; m < MT; m += NGW) rms_row_b2b((const bf16_t*)(ws + WS_X1) + (size_t)m * DM, p.in[18], (bf16_t*)(ws + WS_H2) + (size_t)m * DM, lane);
.LBB0_1174:
	s_cmp_lt_i32 s18, 7
	s_cselect_b64 s[4:5], -1, 0
	s_and_b64 s[4:5], s[4:5], s[0:1]
	s_andn2_b64 vcc, exec, s[4:5]
	s_cbranch_vccnz .LBB0_1179
	s_mov_b64 exec, -1
	v_mbcnt_lo_u32_b32 v0, -1, 0
	v_mbcnt_hi_u32_b32 v0, -1, v0
	s_lshr_b32 s84, s24, 6
	s_lshl_b32 s85, s2, 3
	s_add_i32 s85, s85, s84
	v_readlane_b32 s86, v254, 4
	v_readlane_b32 s87, v254, 5
	v_lshlrev_b32_e32 v1, 5, v0
	v_add_u32_e32 v2, 0x1000, v1
	v_lshlrev_b32_e32 v3, 4, v0
	s_nop 2
	global_load_dwordx4 v[64:67], v1, s[86:87]
	global_load_dwordx4 v[68:71], v1, s[86:87] offset:16
	global_load_dwordx4 v[72:75], v1, s[86:87] offset:2048
	global_load_dwordx4 v[76:79], v1, s[86:87] offset:2064
	global_load_dwordx4 v[80:83], v2, s[86:87]
	global_load_dwordx4 v[84:87], v2, s[86:87] offset:16
	global_load_dwordx4 v[88:91], v2, s[86:87] offset:2048
	global_load_dwordx4 v[92:95], v2, s[86:87] offset:2064
	s_lshl_b32 s88, s85, 12
	s_add_u32 s90, s22, 0x17d2a000
	s_addc_u32 s91, s23, 0
	s_add_u32 s90, s90, s88
	s_addc_u32 s91, s91, 0
	s_add_u32 s92, s90, 0x4200000
	s_addc_u32 s93, s91, 0
	v_mov_b32_e32 v4, 0x358637bd
	v_xor_b32_e32 v5, 1, v0
	v_lshlrev_b32_e32 v5, 2, v5
	v_xor_b32_e32 v6, 2, v0
	v_lshlrev_b32_e32 v6, 2, v6
	v_xor_b32_e32 v7, 4, v0
	v_lshlrev_b32_e32 v7, 2, v7
	v_xor_b32_e32 v8, 8, v0
	v_lshlrev_b32_e32 v8, 2, v8
	v_xor_b32_e32 v9, 16, v0
	v_lshlrev_b32_e32 v9, 2, v9
	v_xor_b32_e32 v10, 32, v0
	v_lshlrev_b32_e32 v10, 2, v10
	global_load_dwordx4 v[24:27], v3, s[90:91]
	global_load_dwordx4 v[28:31], v3, s[90:91] offset:1024
	global_load_dwordx4 v[32:35], v3, s[90:91] offset:2048
	global_load_dwordx4 v[36:39], v3, s[90:91] offset:3072
	s_waitcnt vmcnt(0)
.Lrms6_loop:
	s_add_i32 s94, s85, 0x800
	s_cmp_lt_u32 s94, 0x2100
	s_cbranch_scc0 .Lrms6_nopf
	s_add_u32 s90, s90, 0x800000
	s_addc_u32 s91, s91, 0
	global_load_dwordx4 v[40:43], v3, s[90:91]
	global_load_dwordx4 v[44:47], v3, s[90:91] offset:1024
	global_load_dwordx4 v[48:51], v3, s[90:91] offset:2048
	global_load_dwordx4 v[52:55], v3, s[90:91] offset:3072
.Lrms6_nopf:
	v_lshlrev_b32_e32 v100, 16, v24
	v_and_b32_e32 v101, 0xffff0000, v24
	v_lshlrev_b32_e32 v102, 16, v25
	v_and_b32_e32 v103, 0xffff0000, v25
	v_lshlrev_b32_e32 v104, 16, v26
	v_and_b32_e32 v105, 0xffff0000, v26
	v_lshlrev_b32_e32 v106, 16, v27
	v_and_b32_e32 v107, 0xffff0000, v27
	v_lshlrev_b32_e32 v108, 16, v28
	v_and_b32_e32 v109, 0xffff0000, v28
	v_lshlrev_b32_e32 v110, 16, v29
	v_and_b32_e32 v111, 0xffff0000, v29
	v_lshlrev_b32_e32 v112, 16, v30
	v_and_b32_e32 v113, 0xffff0000, v30
	v_lshlrev_b32_e32 v114, 16, v31
	v_and_b32_e32 v115, 0xffff0000, v31
	v_lshlrev_b32_e32 v116, 16, v32
	v_and_b32_e32 v117, 0xffff0000, v32
	v_lshlrev_b32_e32 v118, 16, v33
	v_and_b32_e32 v119, 0xffff0000, v33
	v_lshlrev_b32_e32 v120, 16, v34
	v_and_b32_e32 v121, 0xffff0000, v34
	v_lshlrev_b32_e32 v122, 16, v35
	v_and_b32_e32 v123, 0xffff0000, v35
	v_lshlrev_b32_e32 v124, 16, v36
	v_and_b32_e32 v125, 0xffff0000, v36
	v_lshlrev_b32_e32 v126, 16, v37
	v_and_b32_e32 v127, 0xffff0000, v37
	v_lshlrev_b32_e32 v128, 16, v38
	v_and_b32_e32 v129, 0xffff0000, v38
	v_lshlrev_b32_e32 v130, 16, v39
	v_and_b32_e32 v131, 0xffff0000, v39
	v_mov_b32_e32 v16, 0
	v_mul_f32_e32 v17, v101, v101
	v_fmac_f32_e32 v17, v100, v100
	v_mul_f32_e32 v18, v103, v103
	v_fmac_f32_e32 v18, v102, v102
	v_mul_f32_e32 v19, v105, v105
	v_fmac_f32_e32 v19, v104, v104
	v_mul_f32_e32 v20, v107, v107
	v_fmac_f32_e32 v20, v106, v106
	v_add_f32_e32 v17, v17, v18
	v_add_f32_e32 v19, v19, v20
	v_add_f32_e32 v17, v17, v19
	v_add_f32_e32 v16, v16, v17
	v_mul_f32_e32 v17, v109, v109
	v_fmac_f32_e32 v17, v108, v108
	v_mul_f32_e32 v18, v111, v111
	v_fmac_f32_e32 v18, v110, v110
	v_mul_f32_e32 v19, v113, v113
	v_fmac_f32_e32 v19, v112, v112
	v_mul_f32_e32 v20, v115, v115
	v_fmac_f32_e32 v20, v114, v114
	v_add_f32_e32 v17, v17, v18
	v_add_f32_e32 v19, v19, v20
	v_add_f32_e32 v17, v17, v19
	v_add_f32_e32 v16, v16, v17
	v_mul_f32_e32 v17, v117, v117
	v_fmac_f32_e32 v17, v116, v116
	v_mul_f32_e32 v18, v119, v119
	v_fmac_f32_e32 v18, v118, v118
	v_mul_f32_e32 v19, v121, v121
	v_fmac_f32_e32 v19, v120, v120
	v_mul_f32_e32 v20, v123, v123
	v_fmac_f32_e32 v20, v122, v122
	v_add_f32_e32 v17, v17, v18
	v_add_f32_e32 v19, v19, v20
	v_add_f32_e32 v17, v17, v19
	v_add_f32_e32 v16, v16, v17
	v_mul_f32_e32 v17, v125, v125
	v_fmac_f32_e32 v17, v124, v124
	v_mul_f32_e32 v18, v127, v127
	v_fmac_f32_e32 v18, v126, v126
	v_mul_f32_e32 v19, v129, v129
	v_fmac_f32_e32 v19, v128, v128
	v_mul_f32_e32 v20, v131, v131
	v_fmac_f32_e32 v20, v130, v130
	v_add_f32_e32 v17, v17, v18
	v_add_f32_e32 v19, v19, v20
	v_add_f32_e32 v17, v17, v19
	v_add_f32_e32 v16, v16, v17
	ds_bpermute_b32 v17, v5, v16
	s_waitcnt lgkmcnt(0)
	v_add_f32_e32 v16, v16, v17
	ds_bpermute_b32 v17, v6, v16
	s_waitcnt lgkmcnt(0)
	v_add_f32_e32 v16, v16, v17
	ds_bpermute_b32 v17, v7, v16
	s_waitcnt lgkmcnt(0)
	v_add_f32_e32 v16, v16, v17
	ds_bpermute_b32 v17, v8, v16
	s_waitcnt lgkmcnt(0)
	v_add_f32_e32 v16, v16, v17
	ds_bpermute_b32 v17, v9, v16
	s_waitcnt lgkmcnt(0)
	v_add_f32_e32 v16, v16, v17
	ds_bpermute_b32 v17, v10, v16
	s_waitcnt lgkmcnt(0)
; #define LAS __attribute__((address_space(3)))
; __device__ __forceinline__ unsigned pk2(float lo, float hi) { const f32x2_t v = {lo, hi}; const bf16x2_t b = __builtin_convertvector(v, bf16x2_t); return __builtin_bit_cast(unsigned, b); }
; __device__ __forceinline__ float bflo(unsigned w) { return __uint_as_float(w << 16); }
; __device__ __forceinline__ float bfhi(unsigned w) { return __uint_as_float(w & 0xffff0000u); }
; __device__ __forceinline__ unsigned xb_ld(unsigned* p)              { return __hip_atomic_load(p, __ATOMIC_RELAXED, __HIP_MEMORY_SCOPE_AGENT); }
; __device__ __forceinline__ unsigned xb_xcc_id() { return (unsigned)__builtin_amdgcn_s_getreg((3 << 11) | 20) & 0xFu; }
; __device__ __forceinline__ void rms_row_b2b(const bf16_t* xrow, const float* g, bf16_t* orow, int lane) {
;     ...
;     const float rstd = rsqrtf(wave_sum(s) * (1.f / DM) + EPS);
;     u32x4* o = (u32x4*)orow + lane;
; #pragma unroll
;     for (int j = 0; j < 4; ++j) { const f32x4 g0 = ((const f32x4*)g)[(64 * j + lane) * 2], g1 = ((const f32x4*)g)[(64 * j + lane) * 2 + 1]; u32x4 r;
;         r.x = pk2(bflo(w[j].x) * rstd * g0.x, bfhi(w[j].x) * rstd * g0.y); r.y = pk2(bflo(w[j].y) * rstd * g0.z, bfhi(w[j].y) * rstd * g0.w);
;         r.z = pk2(bflo(w[j].z) * rstd * g1.x, bfhi(w[j].z) * rstd * g1.y); r.w = pk2(bflo(w[j].w) * rstd * g1.z, bfhi(w[j].w) * rstd * g1.w); o[64 * j] = r; }
; }
; __device__ __forceinline__ void xcd_barrier(unsigned* bar, volatile LAS unsigned* st, int wave_s) {
;     asm volatile("s_waitcnt vmcnt(0)" ::: "memory");
;     __syncthreads();
;     if (opaque_tid(wave_s) == 0) {
;         __builtin_amdgcn_s_waitcnt(0);
;         const unsigned x = xb_xcc_id();
;         unsigned nloc = st[0], nx = st[1];
;         if (nloc == 0u) {
;             const unsigned G = gridDim.x; unsigned sum, cnt, mine;
;             for (;;) { sum = 0u; cnt = 0u; mine = 0u;
; #pragma unroll
;                 for (unsigned j = 0; j < 16; ++j) { const unsigned c = xb_ld(&bar[XB_XCNT(j)]); sum += c; cnt += (c > 0u) ? 1u : 0u; mine = (j == x) ? c : mine; }
;                 if (sum == G) break;
;                 __builtin_amdgcn_s_sleep(1); }
;             nloc = mine > 0u ? mine : 1u; nx = cnt > 0u ? cnt : 1u; st[0] = nloc; st[1] = nx; }
	v_add_f32_e32 v16, v16, v17
	v_fmamk_f32 v16, v16, 0x3a000000, v4
	v_rsq_f32_e32 v16, v16
	s_nop 0
	v_mul_f32_e32 v100, v100, v16
	v_mul_f32_e32 v101, v101, v16
	v_mul_f32_e32 v102, v102, v16
	v_mul_f32_e32 v103, v103, v16
	v_mul_f32_e32 v104, v104, v16
	v_mul_f32_e32 v105, v105, v16
	v_mul_f32_e32 v106, v106, v16
	v_mul_f32_e32 v107, v107, v16
	v_mul_f32_e32 v100, v100, v64
	v_mul_f32_e32 v101, v101, v65
	v_mul_f32_e32 v102, v102, v66
	v_mul_f32_e32 v103, v103, v67
	v_mul_f32_e32 v104, v104, v68
	v_mul_f32_e32 v105, v105, v69
	v_mul_f32_e32 v106, v106, v70
	v_mul_f32_e32 v107, v107, v71
	v_cvt_pk_bf16_f32 v132, v100, v101
	v_cvt_pk_bf16_f32 v133, v102, v103
	v_cvt_pk_bf16_f32 v134, v104, v105
	v_cvt_pk_bf16_f32 v135, v106, v107
	global_store_dwordx4 v3, v[132:135], s[92:93]
	s_nop 1
	v_mul_f32_e32 v108, v108, v16
	v_mul_f32_e32 v109, v109, v16
	v_mul_f32_e32 v110, v110, v16
	v_mul_f32_e32 v111, v111, v16
	v_mul_f32_e32 v112, v112, v16
	v_mul_f32_e32 v113, v113, v16
	v_mul_f32_e32 v114, v114, v16
	v_mul_f32_e32 v115, v115, v16
	v_mul_f32_e32 v108, v108, v72
	v_mul_f32_e32 v109, v109, v73
	v_mul_f32_e32 v110, v110, v74
	v_mul_f32_e32 v111, v111, v75
	v_mul_f32_e32 v112, v112, v76
	v_mul_f32_e32 v113, v113, v77
	v_mul_f32_e32 v114, v114, v78
	v_mul_f32_e32 v115, v115, v79
	v_cvt_pk_bf16_f32 v132, v108, v109
	v_cvt_pk_bf16_f32 v133, v110, v111
	v_cvt_pk_bf16_f32 v134, v112, v113
	v_cvt_pk_bf16_f32 v135, v114, v115
	global_store_dwordx4 v3, v[132:135], s[92:93] offset:1024
	s_nop 1
	v_mul_f32_e32 v116, v116, v16
	v_mul_f32_e32 v117, v117, v16
	v_mul_f32_e32 v118, v118, v16
	v_mul_f32_e32 v119, v119, v16
	v_mul_f32_e32 v120, v120, v16
	v_mul_f32_e32 v121, v121, v16
	v_mul_f32_e32 v122, v122, v16
	v_mul_f32_e32 v123, v123, v16
	v_mul_f32_e32 v116, v116, v80
	v_mul_f32_e32 v117, v117, v81
	v_mul_f32_e32 v118, v118, v82
	v_mul_f32_e32 v119, v119, v83
	v_mul_f32_e32 v120, v120, v84
	v_mul_f32_e32 v121, v121, v85
	v_mul_f32_e32 v122, v122, v86
	v_mul_f32_e32 v123, v123, v87
	v_cvt_pk_bf16_f32 v132, v116, v117
	v_cvt_pk_bf16_f32 v133, v118, v119
	v_cvt_pk_bf16_f32 v134, v120, v121
	v_cvt_pk_bf16_f32 v135, v122, v123
	global_store_dwordx4 v3, v[132:135], s[92:93] offset:2048
	s_nop 1
	v_mul_f32_e32 v124, v124, v16
	v_mul_f32_e32 v125, v125, v16
	v_mul_f32_e32 v126, v126, v16
	v_mul_f32_e32 v127, v127, v16
	v_mul_f32_e32 v128, v128, v16
	v_mul_f32_e32 v129, v129, v16
	v_mul_f32_e32 v130, v130, v16
	v_mul_f32_e32 v131, v131, v16
	v_mul_f32_e32 v124, v124, v88
	v_mul_f32_e32 v125, v125, v89
	v_mul_f32_e32 v126, v126, v90
	v_mul_f32_e32 v127, v127, v91
	v_mul_f32_e32 v128, v128, v92
	v_mul_f32_e32 v129, v129, v93
	v_mul_f32_e32 v130, v130, v94
	v_mul_f32_e32 v131, v131, v95
	v_cvt_pk_bf16_f32 v132, v124, v125
	v_cvt_pk_bf16_f32 v133, v126, v127
	v_cvt_pk_bf16_f32 v134, v128, v129
	v_cvt_pk_bf16_f32 v135, v130, v131
	global_store_dwordx4 v3, v[132:135], s[92:93] offset:3072
	s_nop 1
	s_cmp_lt_u32 s94, 0x2100
	s_cbranch_scc0 .Lrms6_done
	s_waitcnt vmcnt(4)
	v_mov_b64_e32 v[24:25], v[40:41]
	v_mov_b64_e32 v[26:27], v[42:43]
	v_mov_b64_e32 v[28:29], v[44:45]
	v_mov_b64_e32 v[30:31], v[46:47]
	v_mov_b64_e32 v[32:33], v[48:49]
	v_mov_b64_e32 v[34:35], v[50:51]
	v_mov_b64_e32 v[36:37], v[52:53]
	v_mov_b64_e32 v[38:39], v[54:55]
	s_mov_b32 s85, s94
	s_add_u32 s92, s92, 0x800000
	s_addc_u32 s93, s93, 0
	s_branch .Lrms6_loop
.Lrms6_done:
.LBB0_1179:
	s_cmp_gt_i32 s19, 7
	s_cselect_b64 s[0:1], -1, 0
	s_and_b64 s[4:5], s[4:5], s[0:1]
	s_andn2_b64 vcc, exec, s[4:5]
	s_cbranch_vccnz .LBB0_1210
	s_waitcnt vmcnt(0)
	s_waitcnt vmcnt(0)
	s_barrier
	s_mov_b32 s3, 0
	s_nop 0
	v_mbcnt_lo_u32_b32 v0, -1, s3
	v_mbcnt_hi_u32_b32 v0, -1, v0
	v_or_b32_e32 v0, s24, v0
	s_nop 0
	v_cmp_eq_u32_e32 vcc, 0, v0
	s_and_saveexec_b64 s[4:5], vcc
	s_cbranch_execz .LBB0_1209
	s_add_i32 s6, 0, 0x23ff0
	v_mov_b32_e32 v0, s6
	s_waitcnt vmcnt(0) expcnt(0) lgkmcnt(0)
	s_getreg_b32 s3, hwreg(HW_REG_XCC_ID, 0, 4)
	ds_read_b32 v1, v0
	s_add_i32 s6, 0, 0x23ff4
	v_mov_b32_e32 v0, s6
	ds_read_b32 v0, v0
	s_and_b32 s3, s3, 15
	s_waitcnt lgkmcnt(1)
	v_cmp_ne_u32_e32 vcc, 0, v1
	s_cbranch_vccnz .LBB0_1187
	s_add_u32 s6, s22, 0x1f32a400
	s_addc_u32 s7, s23, 0
	s_add_u32 s8, s22, 0x1f32a500
	s_addc_u32 s9, s23, 0
	s_add_u32 s10, s22, 0x1f32a600
	s_addc_u32 s11, s23, 0
	s_add_u32 s12, s22, 0x1f32a700
	s_addc_u32 s13, s23, 0
	s_add_u32 s14, s22, 0x1f32a800
	s_addc_u32 s15, s23, 0
	s_add_u32 s16, s22, 0x1f32a900
	s_addc_u32 s17, s23, 0
	s_add_u32 s26, s22, 0x1f32aa00
	s_addc_u32 s27, s23, 0
	s_add_u32 s28, s22, 0x1f32ab00
	s_addc_u32 s29, s23, 0
	s_add_u32 s30, s22, 0x1f32ac00
	s_addc_u32 s31, s23, 0
	s_add_u32 s34, s22, 0x1f32ad00
	s_addc_u32 s35, s23, 0
	s_add_u32 s36, s22, 0x1f32ae00
	s_addc_u32 s37, s23, 0
	s_add_u32 s38, s22, 0x1f32af00
	s_addc_u32 s39, s23, 0
	s_add_u32 s40, s22, 0x1f32b000
	s_addc_u32 s41, s23, 0
	s_add_u32 s42, s22, 0x1f32b100
	s_addc_u32 s43, s23, 0
	s_add_u32 s44, s22, 0x1f32b200
	s_addc_u32 s45, s23, 0
	s_add_u32 s46, s22, 0x1f32b300
	s_addc_u32 s47, s23, 0
	v_mov_b32_e32 v16, 0
	s_branch .LBB0_1184
